# phase_convert weight transposes: next-tile prefetch de-serialised (8 loads issued together, counted vmcnt before LDS writes, drain before store)
# speedup vs baseline: 1.0022x; 1.0022x over previous
; __device__ void phase_convert(const Params& p, LAS unsigned char* shm, const int part) {
;     ...
;           for (int i = 0; i < 8; ++i) { const int k = (tid >> 6) + 8 * i, n = tid & 63; r[i] = (d.n0 + n < d.N) ? d.src[(size_t)(d.k0 + k) * d.N + d.n0 + n] : 0.f; } };
;       int t = tlo + b;
;       if (t < thi) {
;           TD dc = desc(t); float cur[8]; ldtile(dc, cur);
;           for (;;) {
;               const int tn = t + nb; const bool more = tn < thi; TD dn = dc; float nxt[8];
; #pragma unroll
;               for (int i = 0; i < 8; ++i) nxt[i] = 0.f;
;               if (more) { dn = desc(tn); ldtile(dn, nxt); }
; #pragma unroll
;               for (int i = 0; i < 8; ++i) lds[((tid >> 6) + 8 * i) * 65 + (tid & 63)] = cur[i];
;               __syncthreads();
;               { const int n = tid >> 3, kk0 = (tid & 7) * 8; h16x8 v;
; #pragma unroll
;                 for (int e = 0; e < 8; ++e) v[e] = (h16)lds[(kk0 + e) * 65 + n];
;                 *(h16x8*)(dc.dst + (size_t)(dc.n0 + n) * dc.K + dc.k0 + kk0) = v; }
;               __syncthreads();
.LBB0_113:
	s_ashr_i32 s45, s44, 31
	s_lshl_b64 s[18:19], s[44:45], 2
	s_add_u32 s18, s48, s18
	s_addc_u32 s19, s49, s19
	v_add_u32_e32 v10, s44, v1
	v_mov_b32_e32 v19, v0
	v_cmp_gt_i32_e64 s[0:1], s10, v10
	v_add_u32_e32 v21, s8, v24
	v_lshl_add_u64 v[22:23], s[18:19], 0, v[18:19]
	s_and_saveexec_b64 s[48:49], s[0:1]
	s_cbranch_execz .LtrA_none
	s_lshl_b32 s0, s10, 2
	s_lshl_b32 s18, s10, 5
	s_mov_b32 s19, 0
	v_mad_u64_u32 v[10:11], vcc, v21, s0, v[22:23]
	global_load_dword v2, v[10:11], off
	v_lshl_add_u64 v[10:11], v[10:11], 0, s[18:19]
	global_load_dword v3, v[10:11], off
	v_lshl_add_u64 v[10:11], v[10:11], 0, s[18:19]
	global_load_dword v4, v[10:11], off
	v_lshl_add_u64 v[10:11], v[10:11], 0, s[18:19]
	global_load_dword v5, v[10:11], off
	v_lshl_add_u64 v[10:11], v[10:11], 0, s[18:19]
	global_load_dword v6, v[10:11], off
	v_lshl_add_u64 v[10:11], v[10:11], 0, s[18:19]
	global_load_dword v7, v[10:11], off
	v_lshl_add_u64 v[10:11], v[10:11], 0, s[18:19]
	global_load_dword v8, v[10:11], off
	v_lshl_add_u64 v[10:11], v[10:11], 0, s[18:19]
	global_load_dword v9, v[10:11], off
	s_or_b64 exec, exec, s[48:49]
	s_waitcnt vmcnt(8)
	s_branch .LtrA_write
.LtrA_none:
	s_or_b64 exec, exec, s[48:49]
.LBB0_128:
	s_waitcnt vmcnt(0)
.LtrA_write:
	v_add_u32_e32 v12, 0x400, v35
	ds_write_b32 v34, v26
	ds_write_b32 v34, v27 offset:2080
	ds_write_b32 v34, v25 offset:4160
	ds_write_b32 v34, v28 offset:6240
	ds_write_b32 v34, v30 offset:8320
	ds_write_b32 v34, v31 offset:10400
	ds_write_b32 v34, v29 offset:12480
	ds_write_b32 v34, v32 offset:14560
	s_waitcnt lgkmcnt(0)
	s_barrier
	ds_read2_b32 v[10:11], v12 offset0:134 offset1:199
	ds_read2_b32 v[14:15], v12 offset0:4 offset1:69
	ds_read2_b32 v[16:17], v35 offset0:130 offset1:195
	ds_read2_b32 v[22:23], v35 offset1:65
	s_ashr_i32 s21, s20, 31
	s_waitcnt lgkmcnt(3)
	v_cvt_pk_f16_f32 v13, v10, v11
	s_waitcnt lgkmcnt(2)
	v_cvt_pk_f16_f32 v12, v14, v15
	v_add_u32_e32 v14, s12, v33
	s_waitcnt lgkmcnt(1)
	v_cvt_pk_f16_f32 v11, v16, v17
	v_ashrrev_i32_e32 v17, 31, v14
	v_mad_u64_u32 v[14:15], s[0:1], s5, v14, 0
	v_mov_b32_e32 v16, v15
	v_mad_u64_u32 v[16:17], s[0:1], s5, v17, v[16:17]
	v_mov_b32_e32 v15, v16
	v_lshl_add_u64 v[14:15], v[14:15], 1, s[36:37]
	v_lshl_add_u64 v[14:15], s[20:21], 1, v[14:15]
	v_mov_b32_e32 v21, v0
	s_waitcnt lgkmcnt(0)
	v_cvt_pk_f16_f32 v10, v22, v23
	v_lshl_add_u64 v[14:15], v[14:15], 0, v[20:21]
	s_andn2_b64 vcc, exec, s[42:43]
	s_waitcnt vmcnt(0)
	global_store_dwordx4 v[14:15], v[10:13], off
	s_barrier
	s_cbranch_vccnz .LBB0_101
	v_mov_b32_e32 v32, v9
	v_mov_b32_e32 v29, v8
	v_mov_b32_e32 v31, v7
	v_mov_b32_e32 v30, v6
	v_mov_b32_e32 v28, v5
	v_mov_b32_e32 v25, v4
	v_mov_b32_e32 v27, v3
	v_mov_b32_e32 v26, v2
	s_mov_b32 s12, s44
	s_mov_b32 s20, s8
	s_mov_b32 s5, s9
	s_mov_b64 s[36:37], s[46:47]
	s_mov_b32 s6, s7
	s_branch .LBB0_101

; __device__ void phase_convert(const Params& p, LAS unsigned char* shm, const int part) {
;     ...
;           for (int i = 0; i < 8; ++i) { const int k = (tid >> 6) + 8 * i, n = tid & 63; r[i] = (d.n0 + n < d.N) ? d.src[(size_t)(d.k0 + k) * d.N + d.n0 + n] : 0.f; } };
;       int t = tlo + b;
;       if (t < thi) {
;           TD dc = desc(t); float cur[8]; ldtile(dc, cur);
;           for (;;) {
;               const int tn = t + nb; const bool more = tn < thi; TD dn = dc; float nxt[8];
; #pragma unroll
;               for (int i = 0; i < 8; ++i) nxt[i] = 0.f;
;               if (more) { dn = desc(tn); ldtile(dn, nxt); }
; #pragma unroll
;               for (int i = 0; i < 8; ++i) lds[((tid >> 6) + 8 * i) * 65 + (tid & 63)] = cur[i];
;               __syncthreads();
;               { const int n = tid >> 3, kk0 = (tid & 7) * 8; h16x8 v;
; #pragma unroll
;                 for (int e = 0; e < 8; ++e) v[e] = (h16)lds[(kk0 + e) * 65 + n];
;                 *(h16x8*)(dc.dst + (size_t)(dc.n0 + n) * dc.K + dc.k0 + kk0) = v; }
;               __syncthreads();
.LBB0_442:
	s_ashr_i32 s43, s42, 31
	s_lshl_b64 s[10:11], s[42:43], 2
	s_add_u32 s10, s44, s10
	s_addc_u32 s11, s45, s11
	v_add_u32_e32 v10, s42, v1
	v_mov_b32_e32 v19, v0
	v_cmp_gt_i32_e64 s[0:1], s8, v10
	v_add_u32_e32 v21, s7, v24
	v_lshl_add_u64 v[22:23], s[10:11], 0, v[18:19]
	s_and_saveexec_b64 s[44:45], s[0:1]
	s_cbranch_execz .LtrB_none
	s_lshl_b32 s0, s8, 2
	s_lshl_b32 s10, s8, 5
	s_mov_b32 s11, 0
	v_mad_u64_u32 v[10:11], vcc, v21, s0, v[22:23]
	global_load_dword v2, v[10:11], off
	v_lshl_add_u64 v[10:11], v[10:11], 0, s[10:11]
	global_load_dword v3, v[10:11], off
	v_lshl_add_u64 v[10:11], v[10:11], 0, s[10:11]
	global_load_dword v4, v[10:11], off
	v_lshl_add_u64 v[10:11], v[10:11], 0, s[10:11]
	global_load_dword v5, v[10:11], off
	v_lshl_add_u64 v[10:11], v[10:11], 0, s[10:11]
	global_load_dword v6, v[10:11], off
	v_lshl_add_u64 v[10:11], v[10:11], 0, s[10:11]
	global_load_dword v7, v[10:11], off
	v_lshl_add_u64 v[10:11], v[10:11], 0, s[10:11]
	global_load_dword v8, v[10:11], off
	v_lshl_add_u64 v[10:11], v[10:11], 0, s[10:11]
	global_load_dword v9, v[10:11], off
	s_or_b64 exec, exec, s[44:45]
	s_waitcnt vmcnt(8)
	s_branch .LtrB_write
.LtrB_none:
	s_or_b64 exec, exec, s[44:45]
.LBB0_457:
	s_waitcnt vmcnt(0)
.LtrB_write:
	v_add_u32_e32 v12, 0x400, v36
	ds_write_b32 v35, v26
	ds_write_b32 v35, v27 offset:2080
	ds_write_b32 v35, v25 offset:4160
	ds_write_b32 v35, v28 offset:6240
	ds_write_b32 v35, v30 offset:8320
	ds_write_b32 v35, v31 offset:10400
	ds_write_b32 v35, v29 offset:12480
	ds_write_b32 v35, v32 offset:14560
	s_waitcnt lgkmcnt(0)
	s_barrier
	ds_read2_b32 v[10:11], v12 offset0:134 offset1:199
	ds_read2_b32 v[14:15], v12 offset0:4 offset1:69
	ds_read2_b32 v[16:17], v36 offset0:130 offset1:195
	ds_read2_b32 v[22:23], v36 offset1:65
	s_ashr_i32 s15, s14, 31
	v_mov_b32_e32 v21, v0
	s_waitcnt lgkmcnt(2)
	v_cvt_pk_f16_f32 v12, v14, v15
	v_add_u32_e32 v14, s4, v33
	v_ashrrev_i32_e32 v15, 31, v14
	v_lshlrev_b64 v[14:15], 12, v[14:15]
	v_lshl_add_u64 v[14:15], s[20:21], 0, v[14:15]
	v_lshl_add_u64 v[14:15], s[14:15], 1, v[14:15]
	v_cvt_pk_f16_f32 v13, v10, v11
	s_waitcnt lgkmcnt(1)
	v_cvt_pk_f16_f32 v11, v16, v17
	s_waitcnt lgkmcnt(0)
	v_cvt_pk_f16_f32 v10, v22, v23
	v_lshl_add_u64 v[14:15], v[14:15], 0, v[20:21]
	s_andn2_b64 vcc, exec, s[36:37]
	s_waitcnt vmcnt(0)
	global_store_dwordx4 v[14:15], v[10:13], off
	s_barrier
	s_cbranch_vccnz .LBB0_436
	v_mov_b32_e32 v32, v9
	v_mov_b32_e32 v29, v8
	v_mov_b32_e32 v31, v7
	v_mov_b32_e32 v30, v6
	v_mov_b32_e32 v28, v5
	v_mov_b32_e32 v25, v4
	v_mov_b32_e32 v27, v3
	v_mov_b32_e32 v26, v2
	s_mov_b32 s4, s42
	s_mov_b32 s14, s7
	s_mov_b64 s[20:21], s[40:41]
	s_mov_b32 s5, s6
	s_branch .LBB0_436
